# two-unit GEMM phases: agent-scope stores and no L2 writeback in the seam barrier that follows them
# speedup vs baseline: 1.0091x; 1.0018x over previous
.LBB0_216:
	s_andn2_saveexec_b64 s[14:15], s[14:15]
	s_cbranch_execz .LBB0_236
	s_mov_b64 s[14:15], exec
	s_nop 0
	s_waitcnt lgkmcnt(0)
	s_waitcnt vmcnt(0)
	v_mbcnt_lo_u32_b32 v1, s14, 0
	v_mbcnt_hi_u32_b32 v1, s15, v1
	v_cmp_eq_u32_e32 vcc, 0, v1
	s_and_saveexec_b64 s[16:17], vcc
	s_cbranch_execz .LBB0_219
	s_bcnt1_i32_b64 s3, s[14:15]
	v_mov_b32_e32 v2, 0x3000
	v_mov_b32_e32 v3, s3
	global_atomic_add v2, v2, v3, s[10:11] offset:1024 sc0

.LBB0_667:
	s_andn2_saveexec_b64 s[16:17], s[16:17]
	s_cbranch_execz .LBB0_687
	s_mov_b64 s[16:17], exec
	s_nop 0
	s_waitcnt lgkmcnt(0)
	s_waitcnt vmcnt(0)
	v_mbcnt_lo_u32_b32 v1, s16, 0
	v_mbcnt_hi_u32_b32 v1, s17, v1
	v_cmp_eq_u32_e32 vcc, 0, v1
	s_and_saveexec_b64 s[20:21], vcc
	s_cbranch_execz .LBB0_670
	s_bcnt1_i32_b64 s3, s[16:17]
	v_mov_b32_e32 v2, 0x3000
	v_mov_b32_e32 v3, s3
	global_atomic_add v2, v2, v3, s[12:13] offset:1024 sc0

.LBB0_1238:
	s_andn2_saveexec_b64 s[10:11], s[10:11]
	s_cbranch_execz .LBB0_1258
	s_mov_b64 s[10:11], exec
	s_nop 0
	s_waitcnt lgkmcnt(0)
	s_waitcnt vmcnt(0)
	v_mbcnt_lo_u32_b32 v1, s10, 0
	v_mbcnt_hi_u32_b32 v1, s11, v1
	v_cmp_eq_u32_e32 vcc, 0, v1
	s_and_saveexec_b64 s[12:13], vcc
	s_cbranch_execz .LBB0_1241
	s_bcnt1_i32_b64 s3, s[10:11]
	v_mov_b32_e32 v2, 0x3000
	v_mov_b32_e32 v3, s3
	global_atomic_add v2, v2, v3, s[6:7] offset:1024 sc0
